# GEMM phase start: removed the compiler-inserted s_waitcnt vmcnt(0) before 8 K-loops (K-tile 1's six LDS-DMA loads stay in flight into the first super-phase, as the counted-wait protocol expects)
# baseline (speedup 1.0000x reference)
.LBB0_347:
	s_mov_b64 s[6:7], 0x80
	s_add_i32 m0, s34, 0x18000
	v_lshl_add_u64 v[8:9], v[8:9], 0, s[6:7]
	s_and_b32 s9, s10, 3
	s_lshl_b32 s11, s8, 13
	s_waitcnt vmcnt(2)
	s_barrier
	global_load_lds_dwordx4 v[8:9], off
	v_lshl_add_u64 v[4:5], v[4:5], 0, s[6:7]
	s_add_i32 m0, s34, 0x1a000
	s_add_i32 s38, s34, 0x8000
	s_add_i32 s39, s34, 0xa000
	global_load_lds_dwordx4 v[4:5], off
	v_lshl_add_u64 v[2:3], v[2:3], 0, s[6:7]
	s_mov_b32 m0, s38
	s_add_u32 s12, s28, 0x40080
	global_load_lds_dwordx4 v[2:3], off
	v_lshl_add_u64 v[2:3], v[6:7], 0, s[6:7]
	s_mov_b32 m0, s39
	s_addc_u32 s13, s29, 0
	global_load_lds_dwordx4 v[2:3], off
	s_add_i32 m0, s34, 0x1c000
	v_lshl_add_u64 v[2:3], s[12:13], 0, v[132:133]
	global_load_lds_dwordx4 v[2:3], off
	v_lshl_add_u64 v[2:3], s[12:13], 0, v[136:137]
	s_add_i32 m0, s34, 0x1e000
	s_cmpk_lt_u32 s3, 0x100
	global_load_lds_dwordx4 v[2:3], off
	s_sext_i32_i16 s43, s2
	v_lshl_or_b32 v2, s8, 6, v156
	v_lshl_or_b32 v163, s9, 12, v157
	s_cselect_b64 s[8:9], -1, 0
	s_lshl_b32 s2, s10, 6
	v_lshlrev_b32_e32 v4, 2, v156
	s_bfe_u32 s40, s10, 0x10001
	s_and_b32 s2, s2, 64
	v_readlane_b32 s3, v253, 54
	v_lshl_or_b32 v3, v156, 6, v138
	v_and_b32_e32 v4, 32, v4
	s_add_u32 s2, s3, s2
	v_readlane_b32 s3, v253, 7
	v_bitop3_b32 v6, v3, s11, v4 bitop3:0xde
	v_mov_b32_e32 v3, v133
	s_addc_u32 s3, s3, 0
	v_mov_b32_e32 v139, v133
	v_lshl_add_u64 v[4:5], s[2:3], 0, v[138:139]
	v_lshlrev_b64 v[2:3], 7, v[2:3]
	v_lshl_add_u64 v[140:141], v[4:5], 0, v[2:3]
	v_lshlrev_b32_e32 v2, 8, v0
	v_and_b32_e32 v2, 0x18000, v2
	v_lshlrev_b32_e32 v3, 11, v154
	v_or3_b32 v2, v152, v2, v3
	v_add_u32_e32 v142, v2, v153
	v_lshlrev_b32_e32 v2, 4, v155
	s_waitcnt vmcnt(6)
	v_and_b32_e32 v2, 0x38000, v2
	v_or3_b32 v2, v152, v2, v3
	s_add_i32 s41, 0, 0x10000
	s_add_i32 s42, 0, 0x14000
	v_mov_b32_e32 v143, v133
	v_add_u32_e32 v144, v2, v153
	v_mov_b32_e32 v145, v133
	v_add_u32_e32 v139, s41, v163
	v_add_u32_e32 v164, s42, v163
	v_add_u32_e32 v165, 0, v6
	v_mov_b64_e32 v[146:147], 0xaff
	s_barrier
	s_branch .LBB0_350

.LBB0_484:
	s_lshl_b32 s3, s3, 5
	s_and_b32 s3, s3, 0x60
	s_lshl_b32 s7, s2, 13
	s_lshl_b32 s10, s3, 7
	s_add_u32 s8, s20, 0x8000
	s_addc_u32 s9, s21, 0
	s_add_i32 m0, s29, 0x18000
	v_lshl_add_u64 v[8:9], s[8:9], 0, v[132:133]
	s_waitcnt vmcnt(2)
	s_barrier
	global_load_lds_dwordx4 v[8:9], off
	s_add_i32 m0, s29, 0x1a000
	v_lshl_add_u64 v[8:9], s[8:9], 0, v[136:137]
	s_add_u32 s8, s18, 0x8000
	s_addc_u32 s9, s19, 0
	s_add_i32 s36, s29, 0x8000
	global_load_lds_dwordx4 v[8:9], off
	v_lshl_add_u64 v[8:9], s[8:9], 0, v[130:131]
	s_mov_b32 m0, s36
	s_add_i32 s37, s29, 0xa000
	global_load_lds_dwordx4 v[8:9], off
	v_lshl_add_u64 v[8:9], s[8:9], 0, v[134:135]
	s_add_u32 s8, s20, 0xc000
	s_mov_b32 m0, s37
	s_addc_u32 s9, s21, 0
	global_load_lds_dwordx4 v[8:9], off
	s_add_i32 m0, s29, 0x1c000
	v_lshl_add_u64 v[8:9], s[8:9], 0, v[132:133]
	global_load_lds_dwordx4 v[8:9], off
	v_lshl_add_u64 v[8:9], s[8:9], 0, v[136:137]
	s_add_i32 m0, s29, 0x1e000
	v_and_b32_e32 v4, 0x1800, v4
	global_load_lds_dwordx4 v[8:9], off
	v_and_b32_e32 v8, 15, v0
	v_lshlrev_b32_e32 v5, 7, v5
	v_lshl_or_b32 v146, s2, 6, v8
	v_lshlrev_b32_e32 v9, 1, v6
	v_lshlrev_b32_e32 v10, 2, v0
	v_lshlrev_b32_e32 v11, 6, v0
	s_movk_i32 s2, 0x3c0
	v_or3_b32 v4, v2, v4, v5
	v_lshl_or_b32 v8, v8, 6, v9
	v_and_b32_e32 v10, 32, v10
	v_and_or_b32 v9, v11, s2, v9
	s_waitcnt vmcnt(6)
	s_cmpk_lt_u32 s6, 0x100
	v_add_u32_e32 v138, v4, v3
	v_and_b32_e32 v4, 0x3800, v7
	v_bitop3_b32 v8, v8, s7, v10 bitop3:0xde
	v_bitop3_b32 v147, s10, v9, v10 bitop3:0xf6
	s_cselect_b64 s[6:7], -1, 0
	v_or3_b32 v2, v2, v4, v5
	s_add_i32 s38, 0, 0x10000
	s_add_i32 s39, 0, 0x14000
	v_or_b32_e32 v148, s3, v6
	v_mov_b32_e32 v139, v133
	v_add_u32_e32 v140, v2, v3
	v_mov_b32_e32 v141, v133
	v_add_u32_e32 v149, s38, v147
	v_add_u32_e32 v150, s39, v147
	v_add_u32_e32 v151, 0, v8
	v_mov_b64_e32 v[142:143], 0x1ff
	s_barrier
	s_branch .LBB0_487

.LBB0_548:
	s_lshl_b32 s6, s6, 5
	s_and_b32 s12, s6, 0x60
	s_mov_b64 s[6:7], 0x80
	s_add_i32 m0, s37, 0x18000
	v_lshl_add_u64 v[8:9], v[8:9], 0, s[6:7]
	s_lshl_b32 s9, s8, 13
	s_lshl_b32 s13, s12, 7
	s_waitcnt vmcnt(2)
	s_barrier
	global_load_lds_dwordx4 v[8:9], off
	v_lshl_add_u64 v[6:7], v[6:7], 0, s[6:7]
	s_add_i32 m0, s37, 0x1a000
	s_add_i32 s41, s37, 0x8000
	s_add_i32 s42, s37, 0xa000
	global_load_lds_dwordx4 v[6:7], off
	v_lshl_add_u64 v[2:3], v[2:3], 0, s[6:7]
	s_mov_b32 m0, s41
	s_add_u32 s10, s28, 0x40080
	global_load_lds_dwordx4 v[2:3], off
	v_lshl_add_u64 v[2:3], v[4:5], 0, s[6:7]
	s_mov_b32 m0, s42
	s_addc_u32 s11, s29, 0
	global_load_lds_dwordx4 v[2:3], off
	s_add_i32 m0, s37, 0x1c000
	v_lshl_add_u64 v[2:3], s[10:11], 0, v[134:135]
	global_load_lds_dwordx4 v[2:3], off
	v_lshl_add_u64 v[2:3], s[10:11], 0, v[130:131]
	s_add_i32 m0, s37, 0x1e000
	s_sext_i32_i8 s47, s2
	global_load_lds_dwordx4 v[2:3], off
	v_and_b32_e32 v2, 15, v0
	v_lshlrev_b32_e32 v3, 1, v13
	v_lshlrev_b32_e32 v4, 2, v0
	s_movk_i32 s2, 0x3c0
	v_lshl_or_b32 v148, s8, 6, v2
	v_lshl_or_b32 v2, v2, 6, v3
	v_and_b32_e32 v4, 32, v4
	v_and_or_b32 v3, v146, s2, v3
	v_bitop3_b32 v149, s13, v3, v4 bitop3:0xf6
	v_lshlrev_b32_e32 v3, 8, v0
	v_bitop3_b32 v2, v2, s9, v4 bitop3:0xde
	v_and_b32_e32 v3, 0x18000, v3
	v_lshlrev_b32_e32 v4, 11, v14
	v_or3_b32 v3, v11, v3, v4
	v_add_u32_e32 v138, v3, v12
	v_lshlrev_b32_e32 v3, 4, v10
	s_waitcnt vmcnt(6)
	s_cmpk_lt_u32 s3, 0x100
	v_and_b32_e32 v3, 0x38000, v3
	s_cselect_b64 s[8:9], -1, 0
	v_or3_b32 v3, v11, v3, v4
	s_add_i32 s44, 0, 0x10000
	s_add_i32 s45, 0, 0x14000
	s_ashr_i32 s43, s68, 31
	v_or_b32_e32 v150, s12, v13
	v_mov_b32_e32 v139, v135
	v_add_u32_e32 v140, v3, v12
	v_mov_b32_e32 v141, v135
	v_add_u32_e32 v151, s44, v149
	v_add_u32_e32 v152, s45, v149
	v_add_u32_e32 v153, 0, v2
	s_movk_i32 s46, 0x1800
	v_mov_b64_e32 v[142:143], 0x5ff
	s_barrier
	s_branch .LBB0_551

.LBB0_1087:
	s_lshl_b32 s6, s6, 5
	s_and_b32 s12, s6, 0x60
	s_mov_b64 s[6:7], 0x80
	s_add_i32 m0, s40, 0x18000
	v_lshl_add_u64 v[8:9], v[8:9], 0, s[6:7]
	s_lshl_b32 s9, s3, 13
	s_lshl_b32 s13, s12, 7
	s_waitcnt vmcnt(2)
	s_barrier
	global_load_lds_dwordx4 v[8:9], off
	v_lshl_add_u64 v[4:5], v[4:5], 0, s[6:7]
	s_add_i32 m0, s40, 0x1a000
	s_add_i32 s44, s40, 0x8000
	s_add_i32 s45, s40, 0xa000
	global_load_lds_dwordx4 v[4:5], off
	v_lshl_add_u64 v[2:3], v[2:3], 0, s[6:7]
	s_mov_b32 m0, s44
	s_add_u32 s10, s34, 0x40080
	global_load_lds_dwordx4 v[2:3], off
	v_lshl_add_u64 v[2:3], v[6:7], 0, s[6:7]
	s_mov_b32 m0, s45
	s_addc_u32 s11, s35, 0
	global_load_lds_dwordx4 v[2:3], off
	s_add_i32 m0, s40, 0x1c000
	v_lshl_add_u64 v[2:3], s[10:11], 0, v[132:133]
	global_load_lds_dwordx4 v[2:3], off
	v_lshl_add_u64 v[2:3], s[10:11], 0, v[136:137]
	s_add_i32 m0, s40, 0x1e000
	s_sext_i32_i8 s51, s2
	global_load_lds_dwordx4 v[2:3], off
	v_and_b32_e32 v2, 15, v0
	v_lshlrev_b32_e32 v3, 1, v13
	v_lshlrev_b32_e32 v4, 2, v0
	v_lshlrev_b32_e32 v5, 6, v0
	s_movk_i32 s2, 0x3c0
	v_lshl_or_b32 v1, s3, 6, v2
	v_lshl_or_b32 v2, v2, 6, v3
	v_and_b32_e32 v4, 32, v4
	v_and_or_b32 v3, v5, s2, v3
	v_bitop3_b32 v146, s13, v3, v4 bitop3:0xf6
	v_lshlrev_b32_e32 v3, 8, v0
	v_bitop3_b32 v2, v2, s9, v4 bitop3:0xde
	v_and_b32_e32 v3, 0x18000, v3
	v_lshlrev_b32_e32 v4, 11, v12
	v_or3_b32 v3, v10, v3, v4
	v_add_u32_e32 v138, v3, v11
	v_lshlrev_b32_e32 v3, 4, v14
	s_waitcnt vmcnt(6)
	s_cmpk_lt_u32 s8, 0x100
	v_and_b32_e32 v3, 0x38000, v3
	s_cselect_b64 s[8:9], -1, 0
	v_or3_b32 v3, v10, v3, v4
	s_add_i32 s47, 0, 0x10000
	s_add_i32 s48, 0, 0x14000
	s_ashr_i32 s46, s68, 31
	v_or_b32_e32 v147, s12, v13
	v_mov_b32_e32 v139, v133
	v_add_u32_e32 v140, v3, v11
	v_mov_b32_e32 v141, v133
	v_add_u32_e32 v148, s47, v146
	v_add_u32_e32 v149, s48, v146
	v_add_u32_e32 v150, 0, v2
	s_mov_b64 s[10:11], 0x50000
	s_mov_b32 s49, 0x50000
	s_mov_b64 s[12:13], 0x58000
	s_mov_b32 s50, 0x58000
	v_mov_b64_e32 v[142:143], 0x1ff
	s_barrier
	s_branch .LBB0_1090

.LBB0_1168:
	s_mov_b64 s[10:11], 0x80
	s_and_b32 s2, s0, 3
	s_add_i32 m0, s42, 0x18000
	v_lshl_add_u64 v[8:9], v[8:9], 0, s[10:11]
	s_lshl_b32 s3, s14, 13
	s_lshl_b32 s13, s2, 12
	s_waitcnt vmcnt(2)
	s_barrier
	global_load_lds_dwordx4 v[8:9], off
	v_lshl_add_u64 v[4:5], v[4:5], 0, s[10:11]
	s_add_i32 m0, s42, 0x1a000
	s_add_i32 s47, s42, 0x8000
	s_add_i32 s48, s42, 0xa000
	global_load_lds_dwordx4 v[4:5], off
	v_lshl_add_u64 v[2:3], v[2:3], 0, s[10:11]
	s_mov_b32 m0, s47
	s_add_u32 s0, s38, 0x40080
	global_load_lds_dwordx4 v[2:3], off
	v_lshl_add_u64 v[2:3], v[6:7], 0, s[10:11]
	s_mov_b32 m0, s48
	s_addc_u32 s1, s39, 0
	global_load_lds_dwordx4 v[2:3], off
	s_add_i32 m0, s42, 0x1c000
	v_lshl_add_u64 v[2:3], s[0:1], 0, v[132:133]
	global_load_lds_dwordx4 v[2:3], off
	v_lshl_add_u64 v[2:3], s[0:1], 0, v[136:137]
	s_add_i32 m0, s42, 0x1e000
	v_lshlrev_b32_e32 v7, 2, v0
	global_load_lds_dwordx4 v[2:3], off
	v_bfe_u32 v3, v0, 4, 2
	v_and_b32_e32 v2, 15, v0
	v_lshlrev_b32_e32 v5, 4, v3
	v_lshlrev_b32_e32 v8, 6, v0
	s_movk_i32 s0, 0x3c0
	v_lshl_or_b32 v6, v2, 6, v5
	v_and_b32_e32 v7, 32, v7
	v_and_or_b32 v5, v8, s0, v5
	s_cmpk_lt_u32 s12, 0x100
	v_lshlrev_b32_e32 v4, 3, v3
	v_bitop3_b32 v6, v6, s3, v7 bitop3:0xde
	v_bitop3_b32 v148, s13, v5, v7 bitop3:0xf6
	s_cselect_b64 s[12:13], -1, 0
	s_lshl_b32 s3, s14, 10
	v_lshl_or_b32 v149, s2, 5, v4
	s_lshl_b32 s2, s2, 2
	s_add_i32 s3, s3, 0
	s_add_i32 s2, s3, s2
	v_lshl_or_b32 v1, s14, 6, v2
	v_lshlrev_b32_e32 v2, 4, v2
	s_add_i32 s3, s2, 0x20400
	v_add_u32_e32 v150, s3, v2
	s_add_i32 s3, s2, 0x20500
	v_add_u32_e32 v151, s3, v2
	s_add_i32 s3, s2, 0x20600
	v_add_u32_e32 v152, s3, v2
	s_add_i32 s3, s2, 0x20700
	v_add_u32_e32 v153, s3, v2
	s_add_i32 s3, s2, 0x20c00
	v_add_u32_e32 v154, s3, v2
	s_add_i32 s3, s2, 0x20d00
	v_add_u32_e32 v155, s3, v2
	s_add_i32 s3, s2, 0x20e00
	s_add_i32 s2, s2, 0x20f00
	v_add_u32_e32 v156, s3, v2
	v_add_u32_e32 v157, s2, v2
	v_lshlrev_b32_e32 v2, 8, v0
	v_and_b32_e32 v2, 0x18000, v2
	v_lshlrev_b32_e32 v4, 11, v12
	v_or3_b32 v2, v10, v2, v4
	v_add_u32_e32 v138, v2, v11
	v_lshlrev_b32_e32 v2, 4, v13
	v_and_b32_e32 v2, 0x38000, v2
	v_or3_b32 v2, v10, v2, v4
	s_waitcnt vmcnt(6)
	v_cmp_eq_u32_e64 s[0:1], 0, v3
	v_lshlrev_b32_e32 v3, 4, v1
	v_add_u32_e32 v140, v2, v11
	v_mbcnt_lo_u32_b32 v2, -1, 0
	s_add_i32 s51, 0, 0x10000
	s_add_i32 s52, 0, 0x14000
	v_mbcnt_hi_u32_b32 v161, -1, v2
	v_add_u32_e32 v2, 0, v3
	s_ashr_i32 s49, s68, 31
	s_ashr_i32 s50, s28, 31
	v_mov_b32_e32 v139, v133
	v_mov_b32_e32 v141, v133
	v_add_u32_e32 v158, s51, v148
	v_add_u32_e32 v159, s52, v148
	v_add_u32_e32 v160, 0, v6
	v_add_u32_e32 v162, 0x20400, v2
	s_mov_b32 s53, 0x48000
	s_mov_b64 s[14:15], 0x50000
	s_mov_b32 s54, 0x50000
	s_mov_b64 s[16:17], 0x58000
	s_mov_b32 s55, 0x58000
	v_mov_b64_e32 v[142:143], 0x1ff
	s_barrier
	s_branch .LBB0_1171

.LBB0_1228:
	s_lshl_b32 s8, s8, 5
	s_and_b32 s14, s8, 0x60
	s_mov_b64 s[8:9], 0x80
	s_add_i32 m0, s44, 0x18000
	v_lshl_add_u64 v[8:9], v[8:9], 0, s[8:9]
	s_lshl_b32 s11, s3, 13
	s_lshl_b32 s15, s14, 7
	s_waitcnt vmcnt(2)
	s_barrier
	global_load_lds_dwordx4 v[8:9], off
	v_lshl_add_u64 v[4:5], v[4:5], 0, s[8:9]
	s_add_i32 m0, s44, 0x1a000
	s_add_i32 s48, s44, 0x8000
	s_add_i32 s49, s44, 0xa000
	global_load_lds_dwordx4 v[4:5], off
	v_lshl_add_u64 v[2:3], v[2:3], 0, s[8:9]
	s_mov_b32 m0, s48
	s_add_u32 s12, s38, 0x40080
	global_load_lds_dwordx4 v[2:3], off
	v_lshl_add_u64 v[2:3], v[6:7], 0, s[8:9]
	s_mov_b32 m0, s49
	s_addc_u32 s13, s39, 0
	global_load_lds_dwordx4 v[2:3], off
	s_add_i32 m0, s44, 0x1c000
	v_lshl_add_u64 v[2:3], s[12:13], 0, v[132:133]
	global_load_lds_dwordx4 v[2:3], off
	v_lshl_add_u64 v[2:3], s[12:13], 0, v[136:137]
	s_add_i32 m0, s44, 0x1e000
	s_sext_i32_i8 s57, s2
	global_load_lds_dwordx4 v[2:3], off
	v_and_b32_e32 v2, 15, v0
	v_lshlrev_b32_e32 v3, 1, v13
	v_lshlrev_b32_e32 v4, 2, v0
	v_lshlrev_b32_e32 v5, 6, v0
	s_movk_i32 s2, 0x3c0
	v_lshl_or_b32 v1, s3, 6, v2
	v_lshl_or_b32 v2, v2, 6, v3
	v_and_b32_e32 v4, 32, v4
	v_and_or_b32 v3, v5, s2, v3
	v_bitop3_b32 v146, s15, v3, v4 bitop3:0xf6
	v_lshlrev_b32_e32 v3, 8, v0
	v_bitop3_b32 v2, v2, s11, v4 bitop3:0xde
	v_and_b32_e32 v3, 0x18000, v3
	v_lshlrev_b32_e32 v4, 11, v12
	v_or3_b32 v3, v10, v3, v4
	v_add_u32_e32 v138, v3, v11
	v_lshlrev_b32_e32 v3, 4, v14
	s_waitcnt vmcnt(6)
	s_cmpk_lt_u32 s10, 0x100
	v_and_b32_e32 v3, 0x38000, v3
	s_cselect_b64 s[10:11], -1, 0
	v_or3_b32 v3, v10, v3, v4
	s_add_i32 s51, 0, 0x10000
	s_add_i32 s52, 0, 0x14000
	s_ashr_i32 s50, s68, 31
	v_or_b32_e32 v147, s14, v13
	v_mov_b32_e32 v139, v133
	v_add_u32_e32 v140, v3, v11
	v_mov_b32_e32 v141, v133
	v_add_u32_e32 v148, s51, v146
	v_add_u32_e32 v149, s52, v146
	v_add_u32_e32 v150, 0, v2
	s_mov_b32 s53, 0x40000
	s_mov_b64 s[12:13], 0x48000
	s_mov_b32 s54, 0x48000
	s_mov_b64 s[14:15], 0x50000
	s_mov_b32 s55, 0x50000
	s_mov_b64 s[16:17], 0x58000
	s_mov_b32 s56, 0x58000
	v_mov_b64_e32 v[142:143], 0x1ff
	s_barrier
	s_branch .LBB0_1231

.LBB0_1296:
	s_mov_b64 s[6:7], 0x80
	s_add_i32 m0, s34, 0x18000
	v_lshl_add_u64 v[8:9], v[8:9], 0, s[6:7]
	s_and_b32 s9, s10, 3
	s_lshl_b32 s11, s8, 13
	s_waitcnt vmcnt(2)
	s_barrier
	global_load_lds_dwordx4 v[8:9], off
	v_lshl_add_u64 v[6:7], v[6:7], 0, s[6:7]
	s_add_i32 m0, s34, 0x1a000
	s_add_i32 s39, s34, 0x8000
	s_add_i32 s40, s34, 0xa000
	global_load_lds_dwordx4 v[6:7], off
	v_lshl_add_u64 v[4:5], v[4:5], 0, s[6:7]
	s_mov_b32 m0, s39
	s_add_u32 s12, s28, 0x40080
	global_load_lds_dwordx4 v[4:5], off
	v_lshl_add_u64 v[2:3], v[2:3], 0, s[6:7]
	s_mov_b32 m0, s40
	s_addc_u32 s13, s29, 0
	global_load_lds_dwordx4 v[2:3], off
	s_add_i32 m0, s34, 0x1c000
	v_lshl_add_u64 v[2:3], s[12:13], 0, v[132:133]
	global_load_lds_dwordx4 v[2:3], off
	v_lshl_add_u64 v[2:3], s[12:13], 0, v[136:137]
	s_add_i32 m0, s34, 0x1e000
	s_cmpk_lt_u32 s3, 0x100
	global_load_lds_dwordx4 v[2:3], off
	s_sext_i32_i16 s46, s2
	v_lshl_or_b32 v2, s8, 6, v155
	v_lshl_or_b32 v162, s9, 12, v156
	s_cselect_b64 s[8:9], -1, 0
	s_lshl_b32 s2, s10, 6
	v_lshlrev_b32_e32 v4, 2, v155
	s_bfe_u32 s41, s10, 0x10001
	s_and_b32 s2, s2, 64
	v_readlane_b32 s3, v253, 54
	v_lshl_or_b32 v3, v155, 6, v138
	v_and_b32_e32 v4, 32, v4
	s_add_u32 s2, s3, s2
	v_readlane_b32 s3, v253, 7
	v_bitop3_b32 v6, v3, s11, v4 bitop3:0xde
	v_mov_b32_e32 v3, v133
	s_addc_u32 s3, s3, 0
	v_mov_b32_e32 v139, v133
	v_lshl_add_u64 v[4:5], s[2:3], 0, v[138:139]
	v_lshlrev_b64 v[2:3], 7, v[2:3]
	v_lshl_add_u64 v[140:141], v[4:5], 0, v[2:3]
	v_lshlrev_b32_e32 v2, 8, v0
	v_and_b32_e32 v2, 0x18000, v2
	v_lshlrev_b32_e32 v3, 11, v153
	v_or3_b32 v2, v1, v2, v3
	v_add_u32_e32 v142, v2, v152
	v_lshlrev_b32_e32 v2, 4, v154
	s_waitcnt vmcnt(6)
	v_and_b32_e32 v2, 0x38000, v2
	v_or3_b32 v2, v1, v2, v3
	s_add_i32 s42, 0, 0x10000
	s_add_i32 s43, 0, 0x14000
	v_mov_b32_e32 v143, v133
	v_add_u32_e32 v144, v2, v152
	v_mov_b32_e32 v145, v133
	v_add_u32_e32 v139, s42, v162
	v_add_u32_e32 v163, s43, v162
	v_add_u32_e32 v164, 0, v6
	s_movk_i32 s44, 0x1000
	s_movk_i32 s45, 0x5000
	v_mov_b64_e32 v[146:147], 0xaff
	s_barrier
	s_branch .LBB0_1299

.LBB0_1433:
	s_lshl_b32 s3, s3, 5
	s_and_b32 s3, s3, 0x60
	s_lshl_b32 s7, s2, 13
	s_lshl_b32 s10, s3, 7
	s_add_u32 s8, s28, 0x8000
	s_addc_u32 s9, s29, 0
	s_add_i32 m0, s39, 0x18000
	v_lshl_add_u64 v[8:9], s[8:9], 0, v[132:133]
	s_waitcnt vmcnt(2)
	s_barrier
	global_load_lds_dwordx4 v[8:9], off
	s_add_i32 m0, s39, 0x1a000
	v_lshl_add_u64 v[8:9], s[8:9], 0, v[136:137]
	s_add_u32 s8, s26, 0x8000
	s_addc_u32 s9, s27, 0
	s_add_i32 s44, s39, 0x8000
	global_load_lds_dwordx4 v[8:9], off
	v_lshl_add_u64 v[8:9], s[8:9], 0, v[130:131]
	s_mov_b32 m0, s44
	s_add_i32 s45, s39, 0xa000
	global_load_lds_dwordx4 v[8:9], off
	v_lshl_add_u64 v[8:9], s[8:9], 0, v[134:135]
	s_add_u32 s8, s28, 0xc000
	s_mov_b32 m0, s45
	s_addc_u32 s9, s29, 0
	global_load_lds_dwordx4 v[8:9], off
	s_add_i32 m0, s39, 0x1c000
	v_lshl_add_u64 v[8:9], s[8:9], 0, v[132:133]
	global_load_lds_dwordx4 v[8:9], off
	v_lshl_add_u64 v[8:9], s[8:9], 0, v[136:137]
	s_add_i32 m0, s39, 0x1e000
	v_and_b32_e32 v4, 0x1800, v4
	global_load_lds_dwordx4 v[8:9], off
	v_and_b32_e32 v8, 15, v0
	v_lshlrev_b32_e32 v5, 7, v5
	v_lshl_or_b32 v1, s2, 6, v8
	v_lshlrev_b32_e32 v9, 1, v6
	v_lshlrev_b32_e32 v10, 2, v0
	v_lshlrev_b32_e32 v11, 6, v0
	s_movk_i32 s2, 0x3c0
	v_or3_b32 v4, v2, v4, v5
	v_lshl_or_b32 v8, v8, 6, v9
	v_and_b32_e32 v10, 32, v10
	v_and_or_b32 v9, v11, s2, v9
	s_waitcnt vmcnt(6)
	s_cmpk_lt_u32 s6, 0x100
	v_add_u32_e32 v138, v4, v3
	v_and_b32_e32 v4, 0x3800, v7
	v_bitop3_b32 v8, v8, s7, v10 bitop3:0xde
	v_bitop3_b32 v146, s10, v9, v10 bitop3:0xf6
	s_cselect_b64 s[6:7], -1, 0
	v_or3_b32 v2, v2, v4, v5
	s_add_i32 s46, 0, 0x10000
	s_add_i32 s47, 0, 0x14000
	v_or_b32_e32 v147, s3, v6
	v_mov_b32_e32 v139, v133
	v_add_u32_e32 v140, v2, v3
	v_mov_b32_e32 v141, v133
	v_add_u32_e32 v148, s46, v146
	v_add_u32_e32 v149, s47, v146
	v_add_u32_e32 v150, 0, v8
	s_mov_b64 s[8:9], 0x40000
	s_mov_b32 s48, 0x40000
	s_mov_b64 s[10:11], 0x48000
	s_mov_b32 s49, 0x48000
	s_mov_b64 s[12:13], 0x50000
	s_mov_b32 s50, 0x50000
	s_mov_b64 s[14:15], 0x58000
	s_mov_b32 s51, 0x58000
	v_mov_b64_e32 v[142:143], 0x1ff
	s_barrier
	s_branch .LBB0_1436
